# v92 + phase-0: the SSM workgroups' extra job is a (shorter) transpose instead of an rmsnorm job
# baseline (speedup 1.0000x reference)
.LBB0_19:
	s_cmp_lt_i32 s26, 1
	s_cselect_b64 s[10:11], -1, 0
	s_cmp_gt_i32 s27, 0
	s_cselect_b64 s[0:1], -1, 0
	s_cmpk_lt_i32 s96, 0x440
	s_cselect_b64 s[4:5], -1, 0
	s_and_b64 s[4:5], s[4:5], s[10:11]
	s_and_b64 s[0:1], s[4:5], s[0:1]
	v_writelane_b32 v254, s96, 37
	s_mov_b32 s13, 0
	s_andn2_b64 vcc, exec, s[0:1]
	v_and_b32_e32 v228, 15, v0
	v_writelane_b32 v254, s26, 38
	s_nop 1
	v_writelane_b32 v254, s27, 39
	s_cbranch_vccnz .LBB0_103
	v_and_b32_e32 v1, 0x3ff, v0
	v_lshlrev_b32_e32 v8, 3, v1
	v_and_b32_e32 v4, 0xf8, v8
	v_mul_u32_u24_e32 v6, 0x41, v4
	v_bfe_u32 v89, v0, 5, 5
	v_lshlrev_b32_e32 v6, 2, v6
	s_add_u32 s0, s78, 0x600000
	v_lshlrev_b32_e32 v7, 2, v89
	v_add_u32_e32 v9, 0, v6
	s_addc_u32 s1, s79, 0
	v_add3_u32 v90, 0, v7, v6
	v_add_u32_e32 v91, v9, v7
	v_or_b32_e32 v7, 0x200, v1
	v_bfe_u32 v2, v0, 4, 6
	v_mov_b32_e32 v3, 0xffff9800
	s_add_u32 s92, s78, 0x580000
	v_lshrrev_b32_e32 v92, 5, v7
	v_and_or_b32 v86, v2, 28, v3
	v_lshlrev_b32_e32 v3, 2, v1
	s_addc_u32 s93, s79, 0
	s_movk_i32 s2, 0xf8
	v_lshlrev_b32_e32 v7, 2, v92
	v_and_b32_e32 v5, 0xfc, v3
	s_add_u32 s94, s78, 0x380000
	v_add3_u32 v93, 0, v7, v6
	v_add_u32_e32 v94, v9, v7
	v_or_b32_e32 v7, 0x600, v1
	v_bitop3_b32 v3, v3, s2, v3 bitop3:0xc
	s_addc_u32 s95, s79, 0
	v_lshrrev_b32_e32 v96, 5, v7
	v_add_u32_e32 v101, 0, v3
	v_lshlrev_b32_e32 v3, 6, v1
	v_readlane_b32 s16, v254, 5
	s_mov_b32 s90, s96
	s_add_u32 s96, s78, 0x180000
	v_lshlrev_b32_e32 v7, 2, v96
	v_and_b32_e32 v3, 64, v3
	v_lshlrev_b32_e32 v66, 2, v5
	v_mov_b32_e32 v67, 0
	v_readlane_b32 s17, v254, 6
	v_readlane_b32 s20, v254, 9
	v_readlane_b32 s21, v254, 10
	s_addc_u32 s97, s79, 0
	v_add_u32_e32 v98, v9, v7
	v_mul_u32_u24_e32 v9, 0x78, v1
	v_add_u32_e32 v102, 0, v3
	v_lshlrev_b32_e32 v3, 4, v1
	v_lshl_add_u64 v[68:69], s[16:17], 0, v[66:67]
	v_lshl_add_u64 v[70:71], s[20:21], 0, v[66:67]
	s_add_u32 s14, s78, 0x80000
	v_mul_u32_u24_e32 v11, 0x88, v1
	v_bfe_u32 v100, v1, 4, 2
	v_and_b32_e32 v66, 0x3f0, v3
	v_add3_u32 v3, v9, v8, 0
	s_movk_i32 s2, 0x4200
	s_addc_u32 s15, s79, 0
	v_add_u32_e32 v103, 0x200, v3
	v_add3_u32 v104, v3, v11, s2
	v_lshl_add_u32 v3, v100, 9, 0
	s_add_u32 s80, s78, 0x800000
	v_bfe_u32 v87, v0, 6, 4
	v_add_u32_e32 v107, 0x2200, v3
	v_lshl_add_u32 v3, v228, 3, 0
	s_addc_u32 s81, s79, 0
	v_add_u32_e32 v108, 0x200, v3
	v_lshl_add_u32 v3, v87, 3, 0
	s_add_u32 s34, s78, 0x1600000
	v_add_u32_e32 v109, 0x4200, v3
	v_mbcnt_lo_u32_b32 v3, -1, 0
	s_addc_u32 s35, s79, 0
	v_add_u32_e32 v99, 0, v8
	s_movk_i32 s4, 0x78
	v_mbcnt_hi_u32_b32 v110, -1, v3
	v_readlane_b32 s18, v254, 7
	v_readlane_b32 s19, v254, 8
	v_readlane_b32 s22, v254, 11
	v_readlane_b32 s23, v254, 12
	v_readlane_b32 s24, v254, 13
	v_readlane_b32 s25, v254, 14
	v_readlane_b32 s26, v254, 15
	v_readlane_b32 s27, v254, 16
	v_readlane_b32 s28, v254, 17
	v_readlane_b32 s29, v254, 18
	v_readlane_b32 s30, v254, 19
	v_readlane_b32 s31, v254, 20
	v_writelane_b32 v254, s0, 40
	v_and_b32_e32 v2, 63, v0
	v_add3_u32 v97, 0, v7, v6
	s_add_u32 s52, s78, 0xe800000
	v_mad_u32_u24 v10, v1, s4, v99
	v_lshl_add_u64 v[6:7], s[78:79], 0, v[66:67]
	s_mov_b64 s[4:5], 0x2a00000
	v_lshlrev_b32_e32 v66, 1, v5
	v_and_b32_e32 v3, 64, v110
	v_writelane_b32 v254, s1, 41
	v_lshl_add_u32 v88, v2, 2, 0
	v_or_b32_e32 v95, 32, v89
	s_addc_u32 s53, s79, 0
	v_cmp_gt_u32_e64 s[0:1], 64, v1
	v_lshl_add_u64 v[72:73], v[6:7], 0, s[4:5]
	v_lshl_add_u64 v[74:75], s[76:77], 0, v[66:67]
	v_add_u32_e32 v105, 0x2200, v99
	v_or_b32_e32 v106, 0xfffffe00, v1
	v_add_u32_e32 v111, 64, v3
	v_xor_b32_e32 v112, 32, v110
	v_xor_b32_e32 v113, 16, v110
	s_mov_b32 s54, 0x3a800000
	s_mov_b32 s2, 0x800000
	v_lshlrev_b32_e32 v76, 2, v2
	v_lshlrev_b32_e32 v78, 1, v4
	s_mov_b32 s91, 0x3fb8aa3b
	s_mov_b32 s82, 0xc2ce8ed0
	s_mov_b32 s55, 0x42b17218
	s_mov_b32 s83, 0xdb629599
	s_mov_b32 s84, 0xf534ddc0
	s_mov_b32 s85, 0xfc2757d1
	s_mov_b32 s86, 0x4e441529
	s_mov_b32 s87, 0xa2f9836e
	s_mov_b32 s88, 0x3fc90fda
	s_mov_b32 s89, 0xbfc90fda
	v_mov_b32_e32 v114, 0x3c0881c4
	v_mov_b32_e32 v115, 0xbab64f3b
	v_add_u32_e32 v116, v10, v11
	v_xor_b32_e32 v117, 8, v110
	v_mov_b32_e32 v118, 0x7f800000
	v_not_b32_e32 v119, 63
	v_not_b32_e32 v120, 31
	v_mov_b32_e32 v121, 0x7fc00000
	s_mov_b64 s[56:57], 0x800
	s_mov_b32 s98, s3
	s_movk_i32 s99, 0x440
	s_cmpk_lg_u32 s3, 0x100
	s_cbranch_scc1 .Lp0_bal_done
	s_mov_b32 s98, 0xffffff80
	s_cmpk_lt_u32 s90, 0x80
	s_cbranch_scc0 .Lp0_others
	s_addk_i32 s90, 0x80
	s_branch .Lp0_bal_done
.Lp0_others:
	s_movk_i32 s98, 0x80
	s_addk_i32 s90, 0x80
